# M3 h stage: the 12 per-row denominator reads issued together after the MFMA operand reads (were one at a time with full waits)
# baseline (speedup 1.0000x reference)
.LBB0_733:
	s_or_b64 exec, exec, s[2:3]
	s_waitcnt lgkmcnt(0)
	v_mul_u32_u24_e32 v3, 0x90, v156
	v_lshlrev_b32_e32 v69, 1, v159
	s_waitcnt vmcnt(5)
	v_and_b32_e32 v2, 0xffff, v60
	v_add3_u32 v3, 0, v3, v69
	v_lshrrev_b32_e32 v60, 16, v60
	s_waitcnt vmcnt(4)
	v_lshl_or_b32 v2, v64, 16, v2
	v_and_or_b32 v60, v64, s47, v60
	v_add_u32_e32 v3, 0x8800, v3
	ds_write2_b32 v3, v2, v60 offset1:36
	v_and_b32_e32 v2, 0xffff, v61
	v_lshrrev_b32_e32 v60, 16, v61
	v_lshl_or_b32 v2, v65, 16, v2
	v_and_or_b32 v60, v65, s47, v60
	ds_write2_b32 v3, v2, v60 offset0:72 offset1:108
	v_and_b32_e32 v2, 0xffff, v62
	v_lshrrev_b32_e32 v60, 16, v62
	v_lshl_or_b32 v2, v66, 16, v2
	v_and_or_b32 v60, v66, s47, v60
	ds_write2_b32 v3, v2, v60 offset0:144 offset1:180
	v_and_b32_e32 v2, 0xffff, v63
	v_lshrrev_b32_e32 v60, 16, v63
	s_add_u32 s0, s34, s58
	v_ashrrev_i32_e32 v86, 4, v157
	v_lshl_or_b32 v2, v67, 16, v2
	v_and_or_b32 v60, v67, s47, v60
	s_addc_u32 s1, s35, 0
	v_lshlrev_b32_e32 v82, 1, v156
	v_mov_b32_e32 v83, v0
	v_ashrrev_i32_e32 v87, 31, v86
	ds_write2_b32 v3, v2, v60 offset0:216 offset1:252
	v_lshl_add_u64 v[60:61], s[0:1], 0, v[82:83]
	v_lshl_add_u64 v[84:85], s[26:27], 0, v[86:87]
	v_mad_u64_u32 v[62:63], s[0:1], v84, s33, v[60:61]
	v_mov_b32_e32 v2, v63
	v_mad_u64_u32 v[2:3], s[0:1], v85, s33, v[2:3]
	v_mov_b32_e32 v63, v2
	v_add_u32_e32 v2, 0x200, v157
	v_ashrrev_i32_e32 v2, 4, v2
	v_ashrrev_i32_e32 v3, 31, v2
	v_lshl_add_u64 v[80:81], s[26:27], 0, v[2:3]
	v_mad_u64_u32 v[60:61], s[0:1], v80, s33, v[60:61]
	v_lshlrev_b32_e32 v68, 3, v89
	v_mov_b32_e32 v64, v61
	v_mad_u64_u32 v[64:65], s[0:1], v81, s33, v[64:65]
	v_lshlrev_b32_e32 v3, 1, v68
	v_mul_u32_u24_e32 v68, 0x90, v88
	v_mov_b32_e32 v61, v64
	v_add3_u32 v83, s50, v3, v68
	global_load_dwordx4 v[64:67], v[62:63], off
	s_nop 0
	global_load_dwordx4 v[60:63], v[60:61], off
	s_waitcnt lgkmcnt(0)
	s_barrier
	ds_read_b128 v[68:71], v83
	v_lshl_or_b32 v72, v91, 4, v88
	v_mul_lo_u32 v72, v72, s52
	v_add3_u32 v3, 0, v72, v3
	ds_read_b128 v[72:75], v3 offset:34816
	ds_read_b128 v[92:95], v3 offset:34880
	ds_read_b128 v[76:79], v83 offset:64
	ds_read_b128 v[96:99], v83 offset:2304
	ds_read_b128 v[100:103], v83 offset:2368
	ds_read_b128 v[104:107], v83 offset:4608
	ds_read_b128 v[108:111], v83 offset:4672
	ds_read_b128 v[112:115], v83 offset:6912
	ds_read_b128 v[116:119], v83 offset:6976
	s_waitcnt lgkmcnt(8)
	v_mfma_f32_16x16x32_bf16 v[68:71], v[68:71], v[72:75], 0
	v_and_b32_e32 v3, 48, v157
	v_mul_u32_u24_e32 v83, 0x110, v88
	v_add3_u32 v3, 0, v3, v83
	s_waitcnt lgkmcnt(5)
	v_mfma_f32_16x16x32_bf16 v[96:99], v[96:99], v[72:75], 0
	v_lshl_add_u32 v91, v91, 2, s54
	s_waitcnt lgkmcnt(3)
	v_mfma_f32_16x16x32_bf16 v[104:107], v[104:107], v[72:75], 0
	s_waitcnt lgkmcnt(1)
	v_mfma_f32_16x16x32_bf16 v[112:115], v[112:115], v[72:75], 0
	v_mfma_f32_16x16x32_bf16 v[120:123], v[76:79], v[92:95], v[68:71]
	v_mfma_f32_16x16x32_bf16 v[76:79], v[100:103], v[92:95], v[96:99]
	v_mfma_f32_16x16x32_bf16 v[72:75], v[108:111], v[92:95], v[104:107]
	s_waitcnt lgkmcnt(0)
	v_mfma_f32_16x16x32_bf16 v[68:71], v[116:119], v[92:95], v[112:115]
	ds_read_b128 v[92:95], v3
	ds_read_b128 v[96:99], v3 offset:64
	ds_read_b128 v[100:103], v3 offset:4352
	ds_read_b128 v[104:107], v3 offset:4416
	ds_read_b128 v[108:111], v3 offset:8704
	ds_read_b128 v[112:115], v3 offset:8768
	ds_read_b128 v[116:119], v3 offset:13056
	ds_read_b128 v[124:127], v3 offset:13120
	s_waitcnt vmcnt(5) lgkmcnt(7)
	v_mfma_f32_16x16x32_bf16 v[92:95], v[92:95], v[56:59], 0
	s_waitcnt lgkmcnt(5)
	v_mfma_f32_16x16x32_bf16 v[100:103], v[100:103], v[56:59], 0
	s_waitcnt lgkmcnt(3)
	v_mfma_f32_16x16x32_bf16 v[108:111], v[108:111], v[56:59], 0
	s_waitcnt lgkmcnt(1)
	v_mfma_f32_16x16x32_bf16 v[56:59], v[116:119], v[56:59], 0
	s_waitcnt vmcnt(4)
	v_mfma_f32_16x16x32_bf16 v[92:95], v[96:99], v[52:55], v[92:95]
	v_mfma_f32_16x16x32_bf16 v[96:99], v[104:107], v[52:55], v[100:103]
	v_mfma_f32_16x16x32_bf16 v[100:103], v[112:115], v[52:55], v[108:111]
	s_waitcnt lgkmcnt(0)
	v_mfma_f32_16x16x32_bf16 v[52:55], v[124:127], v[52:55], v[56:59]
	s_nop 2
	ds_read_b128 v[56:59], v3 offset:128
	ds_read_b128 v[104:107], v3 offset:192
	s_waitcnt vmcnt(3) lgkmcnt(1)
	v_mfma_f32_16x16x32_bf16 v[56:59], v[56:59], v[48:51], v[92:95]
	s_nop 2
	ds_read_b128 v[92:95], v3 offset:4480
	ds_read_b128 v[108:111], v3 offset:4544
	s_waitcnt lgkmcnt(1)
	v_mfma_f32_16x16x32_bf16 v[92:95], v[92:95], v[48:51], v[96:99]
	s_nop 2
	ds_read_b128 v[96:99], v3 offset:8832
	ds_read_b128 v[112:115], v3 offset:8896
	s_waitcnt lgkmcnt(1)
	v_mfma_f32_16x16x32_bf16 v[96:99], v[96:99], v[48:51], v[100:103]
	s_nop 2
	ds_read_b128 v[100:103], v3 offset:13184
	ds_read_b128 v[116:119], v3 offset:13248
	v_lshl_add_u32 v3, v90, 2, 0
	v_add_u32_e32 v83, 0x17f00, v3
	s_waitcnt vmcnt(2)
	v_mfma_f32_16x16x32_bf16 v[104:107], v[104:107], v[44:47], v[56:59]
	s_nop 2
	v_add_u32_e32 v56, 0x17e00, v3
	v_lshl_add_u32 v57, v89, 6, s53
	s_waitcnt lgkmcnt(1)
	v_mfma_f32_16x16x32_bf16 v[100:103], v[100:103], v[48:51], v[52:55]
	v_add_u32_e32 v3, 0x18000, v3
	v_mfma_f32_16x16x32_bf16 v[52:55], v[108:111], v[44:47], v[92:95]
	v_mfma_f32_16x16x32_bf16 v[48:51], v[112:115], v[44:47], v[96:99]
	s_nop 2
	ds_read_b128 v[162:165], v57 offset:16
	ds_read_b128 v[166:169], v57 offset:32
	ds_read_b128 v[170:173], v57 offset:48
	ds_read_b128 v[174:177], v57 offset:272
	ds_read_b128 v[178:181], v57 offset:288
	ds_read_b128 v[182:185], v57 offset:304
	ds_read_b128 v[186:189], v57 offset:528
	ds_read_b128 v[190:193], v57 offset:544
	ds_read_b128 v[194:197], v57 offset:560
	ds_read_b128 v[198:201], v57 offset:784
	ds_read_b128 v[202:205], v57 offset:800
	ds_read_b128 v[206:209], v57 offset:816
	ds_read_b128 v[94:97], v56
	ds_read_b128 v[56:59], v57
	ds_read_b128 v[108:111], v83
	ds_read_b128 v[112:115], v3
	v_mov_b32_e32 v93, v0
	s_waitcnt lgkmcnt(4)
	v_mfma_f32_16x16x32_bf16 v[44:47], v[116:119], v[44:47], v[100:103]
	s_waitcnt lgkmcnt(3)
	v_mul_f32_e32 v97, 0xbfb8aa3b, v97
	s_waitcnt lgkmcnt(2)
	v_add_f32_e32 v3, v56, v57
	v_mul_f32_e32 v56, 0xbfb8aa3b, v94
	v_exp_f32_e32 v56, v56
	v_add_f32_e32 v57, v58, v59
	v_add_f32_e32 v3, v3, v57
	s_waitcnt lgkmcnt(0)
	v_fmac_f32_e32 v3, v108, v112
	v_max_f32_e64 v3, |v3|, v56
	v_rcp_f32_e32 v3, v3
	v_fma_f32 v56, v104, v108, v120
	v_mov_b32_e32 v57, v0
	v_mul_f32_e32 v59, 0xbfb8aa3b, v95
	v_mul_f32_e32 v56, v56, v3
	v_mul_f32_e32 v3, v56, v56
	v_exp_f32_e32 v59, v59
	v_exp_f32_e32 v97, v97
	v_mov_b32_dpp v57, v3 row_ror:8 row_mask:0xf bank_mask:0xf
	v_or_b32_e32 v3, 1, v90
	v_lshl_add_u32 v58, v3, 4, s53
	v_fmac_f32_e32 v57, v56, v56
	v_fmac_f32_e32 v123, v107, v111
	v_mov_b32_e32 v95, v0
	v_add_f32_dpp v57, v57, v57 row_ror:4 row_mask:0xf bank_mask:0xf bound_ctrl:1
	s_waitcnt lgkmcnt(0)
	v_add_f32_e32 v83, v164, v165
	v_add_f32_dpp v92, v57, v57 row_ror:2 row_mask:0xf bank_mask:0xf bound_ctrl:1
	v_or_b32_e32 v57, 2, v90
	v_lshl_add_u32 v58, v57, 4, s53
	v_add_f32_e32 v58, v162, v163
	v_add_f32_e32 v58, v58, v83
	v_fmac_f32_e32 v58, v109, v113
	v_max_f32_e64 v58, |v58|, v59
	v_rcp_f32_e32 v58, v58
	v_fma_f32 v59, v105, v109, v121
	v_mov_b32_e32 v83, v0
	s_waitcnt lgkmcnt(0)
	v_add_f32_e32 v87, v168, v169
	v_mul_f32_e32 v59, v59, v58
	v_mul_f32_e32 v58, v59, v59
	v_mov_b32_dpp v93, v92 row_ror:1 row_mask:0xf bank_mask:0xf
	s_nop 0
	v_mov_b32_dpp v83, v58 row_ror:8 row_mask:0xf bank_mask:0xf
	v_fmac_f32_e32 v83, v59, v59
	s_nop 1
	v_add_f32_dpp v58, v83, v83 row_ror:4 row_mask:0xf bank_mask:0xf bound_ctrl:1
	v_mul_f32_e32 v83, 0xbfb8aa3b, v96
	v_exp_f32_e32 v83, v83
	v_add_f32_dpp v94, v58, v58 row_ror:2 row_mask:0xf bank_mask:0xf bound_ctrl:1
	v_add_f32_e32 v58, v166, v167
	v_add_f32_e32 v58, v58, v87
	v_fmac_f32_e32 v58, v110, v114
	v_max_f32_e64 v58, |v58|, v83
	v_rcp_f32_e32 v58, v58
	v_or_b32_e32 v87, 3, v90
	v_fma_f32 v83, v106, v110, v122
	v_lshl_add_u32 v98, v87, 4, s53
	v_mul_f32_e32 v58, v83, v58
	v_mul_f32_e32 v83, v58, v58
	v_mov_b32_e32 v96, v0
	v_mov_b32_dpp v95, v94 row_ror:1 row_mask:0xf bank_mask:0xf
	s_nop 0
	v_mov_b32_dpp v96, v83 row_ror:8 row_mask:0xf bank_mask:0xf
	v_fmac_f32_e32 v96, v58, v58
	s_nop 1
	v_add_f32_dpp v83, v96, v96 row_ror:4 row_mask:0xf bank_mask:0xf bound_ctrl:1
	s_nop 1
	v_add_f32_dpp v96, v83, v83 row_ror:2 row_mask:0xf bank_mask:0xf bound_ctrl:1
	s_waitcnt lgkmcnt(0)
	v_add_f32_e32 v83, v170, v171
	v_add_f32_e32 v98, v172, v173
	v_add_f32_e32 v83, v83, v98
	v_fmac_f32_e32 v83, v111, v115
	v_max_f32_e64 v83, |v83|, v97
	v_rcp_f32_e32 v83, v83
	v_mov_b32_e32 v99, v0
	v_mov_b32_e32 v97, v0
	v_mul_f32_e32 v83, v123, v83
	v_mul_f32_e32 v98, v83, v83
	v_mov_b32_dpp v97, v96 row_ror:1 row_mask:0xf bank_mask:0xf
	s_nop 0
	v_mov_b32_dpp v99, v98 row_ror:8 row_mask:0xf bank_mask:0xf
	v_fmac_f32_e32 v99, v83, v83
	s_nop 1
	v_add_f32_dpp v98, v99, v99 row_ror:4 row_mask:0xf bank_mask:0xf bound_ctrl:1
	v_mov_b32_e32 v99, v0
	s_nop 0
	v_add_f32_dpp v98, v98, v98 row_ror:2 row_mask:0xf bank_mask:0xf bound_ctrl:1
	s_nop 1
	v_mov_b32_dpp v99, v98 row_ror:1 row_mask:0xf bank_mask:0xf
	s_and_saveexec_b64 s[0:1], s[12:13]
	s_cbranch_execz .LBB0_735
	v_add_f32_e32 v92, v92, v93
	v_lshl_add_u32 v93, v89, 7, v91
	v_add_f32_e32 v94, v94, v95
	ds_write_b32 v93, v92
	v_lshl_add_u32 v92, v3, 5, v91
	v_add_f32_e32 v96, v96, v97
	ds_write_b32 v92, v94
	v_lshl_add_u32 v92, v57, 5, v91
	v_add_f32_e32 v98, v98, v99
	ds_write_b32 v92, v96
	v_lshl_add_u32 v92, v87, 5, v91
	ds_write_b32 v92, v98
.LBB0_735:
	s_or_b64 exec, exec, s[0:1]
	v_or_b32_e32 v92, 16, v90
	v_lshl_add_u32 v93, v92, 2, 0
	v_add_u32_e32 v94, 0x17e00, v93
	v_lshl_add_u32 v95, v92, 4, s53
	ds_read_b128 v[96:99], v94
	ds_read_b128 v[100:103], v95
	v_add_u32_e32 v94, 0x17f00, v93
	v_add_u32_e32 v93, 0x18000, v93
	ds_read_b128 v[104:107], v94
	ds_read_b128 v[108:111], v93
	s_waitcnt lgkmcnt(3)
	v_mul_f32_e32 v94, 0xbfb8aa3b, v96
	v_exp_f32_e32 v94, v94
	s_waitcnt lgkmcnt(2)
	v_add_f32_e32 v93, v100, v101
	v_add_f32_e32 v95, v102, v103
	v_add_f32_e32 v93, v93, v95
	s_waitcnt lgkmcnt(0)
	v_fmac_f32_e32 v93, v104, v108
	v_max_f32_e64 v93, |v93|, v94
	v_rcp_f32_e32 v93, v93
	v_fma_f32 v52, v52, v104, v76
	v_mul_f32_e32 v96, 0xbfb8aa3b, v97
	v_exp_f32_e32 v96, v96
	v_mul_f32_e32 v52, v52, v93
	v_mul_f32_e32 v76, v52, v52
	v_mov_b32_e32 v93, v0
	v_fma_f32 v53, v53, v105, v77
	v_fma_f32 v54, v54, v106, v78
	v_mov_b32_dpp v93, v76 row_ror:8 row_mask:0xf bank_mask:0xf
	v_fmac_f32_e32 v93, v52, v52
	v_or_b32_e32 v78, 19, v90
	v_mul_f32_e32 v99, 0xbfb8aa3b, v99
	v_add_f32_dpp v76, v93, v93 row_ror:4 row_mask:0xf bank_mask:0xf bound_ctrl:1
	v_or_b32_e32 v93, 17, v90
	v_lshl_add_u32 v94, v93, 4, s53
	v_exp_f32_e32 v99, v99
	v_add_f32_dpp v94, v76, v76 row_ror:2 row_mask:0xf bank_mask:0xf bound_ctrl:1
	v_or_b32_e32 v76, 18, v90
	v_lshl_add_u32 v95, v76, 4, s53
	s_waitcnt lgkmcnt(1)
	v_add_f32_e32 v95, v174, v175
	v_add_f32_e32 v97, v176, v177
	v_add_f32_e32 v95, v95, v97
	v_fmac_f32_e32 v95, v105, v109
	v_max_f32_e64 v95, |v95|, v96
	v_rcp_f32_e32 v96, v95
	v_mul_f32_e32 v97, 0xbfb8aa3b, v98
	v_exp_f32_e32 v97, v97
	s_waitcnt lgkmcnt(0)
	v_add_f32_e32 v98, v180, v181
	v_mul_f32_e32 v77, v53, v96
	v_mul_f32_e32 v53, v77, v77
	v_mov_b32_e32 v96, v0
	v_lshl_add_u32 v100, v78, 4, s53
	v_mov_b32_dpp v96, v53 row_ror:8 row_mask:0xf bank_mask:0xf
	v_fmac_f32_e32 v96, v77, v77
	v_fmac_f32_e32 v79, v55, v107
	v_mov_b32_e32 v95, v0
	v_add_f32_dpp v53, v96, v96 row_ror:4 row_mask:0xf bank_mask:0xf bound_ctrl:1
	s_nop 0
	v_mov_b32_dpp v95, v94 row_ror:1 row_mask:0xf bank_mask:0xf
	v_add_f32_dpp v96, v53, v53 row_ror:2 row_mask:0xf bank_mask:0xf bound_ctrl:1
	v_add_f32_e32 v53, v178, v179
	v_add_f32_e32 v53, v53, v98
	v_fmac_f32_e32 v53, v106, v110
	v_max_f32_e64 v53, |v53|, v97
	v_rcp_f32_e32 v53, v53
	v_mov_b32_e32 v98, v0
	v_mov_b32_e32 v97, v0
	v_mul_f32_e32 v53, v54, v53
	v_mul_f32_e32 v54, v53, v53
	v_mov_b32_dpp v97, v96 row_ror:1 row_mask:0xf bank_mask:0xf
	s_nop 0
	v_mov_b32_dpp v98, v54 row_ror:8 row_mask:0xf bank_mask:0xf
	v_fmac_f32_e32 v98, v53, v53
	s_nop 1
	v_add_f32_dpp v54, v98, v98 row_ror:4 row_mask:0xf bank_mask:0xf bound_ctrl:1
	s_nop 1
	v_add_f32_dpp v98, v54, v54 row_ror:2 row_mask:0xf bank_mask:0xf bound_ctrl:1
	s_waitcnt lgkmcnt(0)
	v_add_f32_e32 v54, v182, v183
	v_add_f32_e32 v100, v184, v185
	v_add_f32_e32 v54, v54, v100
	v_fmac_f32_e32 v54, v107, v111
	v_max_f32_e64 v54, |v54|, v99
	v_rcp_f32_e32 v54, v54
	v_mov_b32_e32 v99, v0
	v_mul_f32_e32 v54, v79, v54
	v_mul_f32_e32 v55, v54, v54
	v_mov_b32_e32 v79, v0
	v_mov_b32_dpp v99, v98 row_ror:1 row_mask:0xf bank_mask:0xf
	s_nop 0
	v_mov_b32_dpp v79, v55 row_ror:8 row_mask:0xf bank_mask:0xf
	v_fmac_f32_e32 v79, v54, v54
	s_nop 1
	v_add_f32_dpp v55, v79, v79 row_ror:4 row_mask:0xf bank_mask:0xf bound_ctrl:1
	v_mov_b32_e32 v79, v0
	s_nop 0
	v_add_f32_dpp v55, v55, v55 row_ror:2 row_mask:0xf bank_mask:0xf bound_ctrl:1
	s_nop 1
	v_mov_b32_dpp v79, v55 row_ror:1 row_mask:0xf bank_mask:0xf
	s_and_saveexec_b64 s[0:1], s[12:13]
	s_cbranch_execz .LBB0_737
	v_add_f32_e32 v94, v94, v95
	v_lshl_add_u32 v95, v92, 5, v91
	v_add_f32_e32 v96, v96, v97
	ds_write_b32 v95, v94
	v_lshl_add_u32 v94, v93, 5, v91
	v_add_f32_e32 v55, v55, v79
	v_add_f32_e32 v79, v98, v99
	ds_write_b32 v94, v96
	v_lshl_add_u32 v94, v76, 5, v91
	ds_write_b32 v94, v79
	v_lshl_add_u32 v79, v78, 5, v91
	ds_write_b32 v79, v55
.LBB0_737:
	s_or_b64 exec, exec, s[0:1]
	v_or_b32_e32 v55, 32, v90
	v_lshl_add_u32 v79, v55, 2, 0
	v_add_u32_e32 v94, 0x17e00, v79
	v_lshl_add_u32 v95, v55, 4, s53
	ds_read_b128 v[96:99], v94
	ds_read_b128 v[100:103], v95
	v_add_u32_e32 v94, 0x17f00, v79
	v_add_u32_e32 v79, 0x18000, v79
	ds_read_b128 v[104:107], v94
	ds_read_b128 v[108:111], v79
	s_waitcnt lgkmcnt(3)
	v_mul_f32_e32 v94, 0xbfb8aa3b, v96
	v_exp_f32_e32 v94, v94
	s_waitcnt lgkmcnt(2)
	v_add_f32_e32 v79, v100, v101
	v_add_f32_e32 v95, v102, v103
	v_add_f32_e32 v79, v79, v95
	s_waitcnt lgkmcnt(0)
	v_fmac_f32_e32 v79, v104, v108
	v_max_f32_e64 v79, |v79|, v94
	v_rcp_f32_e32 v79, v79
	v_fma_f32 v48, v48, v104, v72
	v_mul_f32_e32 v96, 0xbfb8aa3b, v97
	v_exp_f32_e32 v96, v96
	v_mul_f32_e32 v48, v48, v79
	v_mul_f32_e32 v72, v48, v48
	v_mov_b32_e32 v79, v0
	v_fma_f32 v49, v49, v105, v73
	v_fma_f32 v50, v50, v106, v74
	v_mov_b32_dpp v79, v72 row_ror:8 row_mask:0xf bank_mask:0xf
	v_fmac_f32_e32 v79, v48, v48
	v_or_b32_e32 v74, 35, v90
	v_mul_f32_e32 v99, 0xbfb8aa3b, v99
	v_add_f32_dpp v72, v79, v79 row_ror:4 row_mask:0xf bank_mask:0xf bound_ctrl:1
	v_or_b32_e32 v79, 33, v90
	v_lshl_add_u32 v94, v79, 4, s53
	v_exp_f32_e32 v99, v99
	v_add_f32_dpp v94, v72, v72 row_ror:2 row_mask:0xf bank_mask:0xf bound_ctrl:1
	v_or_b32_e32 v72, 34, v90
	v_lshl_add_u32 v95, v72, 4, s53
	s_waitcnt lgkmcnt(1)
	v_add_f32_e32 v95, v186, v187
	v_add_f32_e32 v97, v188, v189
	v_add_f32_e32 v95, v95, v97
	v_fmac_f32_e32 v95, v105, v109
	v_max_f32_e64 v95, |v95|, v96
	v_rcp_f32_e32 v96, v95
	v_mul_f32_e32 v97, 0xbfb8aa3b, v98
	v_exp_f32_e32 v97, v97
	s_waitcnt lgkmcnt(0)
	v_add_f32_e32 v98, v192, v193
	v_mul_f32_e32 v73, v49, v96
	v_mul_f32_e32 v49, v73, v73
	v_mov_b32_e32 v96, v0
	v_lshl_add_u32 v100, v74, 4, s53
	v_mov_b32_dpp v96, v49 row_ror:8 row_mask:0xf bank_mask:0xf
	v_fmac_f32_e32 v96, v73, v73
	v_fmac_f32_e32 v75, v51, v107
	v_mov_b32_e32 v95, v0
	v_add_f32_dpp v49, v96, v96 row_ror:4 row_mask:0xf bank_mask:0xf bound_ctrl:1
	s_nop 0
	v_mov_b32_dpp v95, v94 row_ror:1 row_mask:0xf bank_mask:0xf
	v_add_f32_dpp v96, v49, v49 row_ror:2 row_mask:0xf bank_mask:0xf bound_ctrl:1
	v_add_f32_e32 v49, v190, v191
	v_add_f32_e32 v49, v49, v98
	v_fmac_f32_e32 v49, v106, v110
	v_max_f32_e64 v49, |v49|, v97
	v_rcp_f32_e32 v49, v49
	v_mov_b32_e32 v98, v0
	v_mov_b32_e32 v97, v0
	v_mul_f32_e32 v49, v50, v49
	v_mul_f32_e32 v50, v49, v49
	v_mov_b32_dpp v97, v96 row_ror:1 row_mask:0xf bank_mask:0xf
	s_nop 0
	v_mov_b32_dpp v98, v50 row_ror:8 row_mask:0xf bank_mask:0xf
	v_fmac_f32_e32 v98, v49, v49
	s_nop 1
	v_add_f32_dpp v50, v98, v98 row_ror:4 row_mask:0xf bank_mask:0xf bound_ctrl:1
	s_nop 1
	v_add_f32_dpp v98, v50, v50 row_ror:2 row_mask:0xf bank_mask:0xf bound_ctrl:1
	s_waitcnt lgkmcnt(0)
	v_add_f32_e32 v50, v194, v195
	v_add_f32_e32 v100, v196, v197
	v_add_f32_e32 v50, v50, v100
	v_fmac_f32_e32 v50, v107, v111
	v_max_f32_e64 v50, |v50|, v99
	v_rcp_f32_e32 v50, v50
	v_mov_b32_e32 v99, v0
	v_mul_f32_e32 v50, v75, v50
	v_mul_f32_e32 v51, v50, v50
	v_mov_b32_e32 v75, v0
	v_mov_b32_dpp v99, v98 row_ror:1 row_mask:0xf bank_mask:0xf
	s_nop 0
	v_mov_b32_dpp v75, v51 row_ror:8 row_mask:0xf bank_mask:0xf
	v_fmac_f32_e32 v75, v50, v50
	s_nop 1
	v_add_f32_dpp v51, v75, v75 row_ror:4 row_mask:0xf bank_mask:0xf bound_ctrl:1
	v_mov_b32_e32 v75, v0
	s_nop 0
	v_add_f32_dpp v51, v51, v51 row_ror:2 row_mask:0xf bank_mask:0xf bound_ctrl:1
	s_nop 1
	v_mov_b32_dpp v75, v51 row_ror:1 row_mask:0xf bank_mask:0xf
	s_and_saveexec_b64 s[0:1], s[12:13]
	s_cbranch_execz .LBB0_739
	v_add_f32_e32 v94, v94, v95
	v_lshl_add_u32 v95, v55, 5, v91
	v_add_f32_e32 v96, v96, v97
	ds_write_b32 v95, v94
	v_lshl_add_u32 v94, v79, 5, v91
	v_add_f32_e32 v51, v51, v75
	v_add_f32_e32 v75, v98, v99
	ds_write_b32 v94, v96
	v_lshl_add_u32 v94, v72, 5, v91
	ds_write_b32 v94, v75
	v_lshl_add_u32 v75, v74, 5, v91
	ds_write_b32 v75, v51
.LBB0_739:
	s_or_b64 exec, exec, s[0:1]
	v_or_b32_e32 v75, 48, v90
	v_lshl_add_u32 v51, v75, 2, 0
	v_add_u32_e32 v94, 0x17e00, v51
	v_lshl_add_u32 v95, v75, 4, s53
	ds_read_b128 v[100:103], v94
	ds_read_b128 v[94:97], v95
	v_add_u32_e32 v98, 0x17f00, v51
	v_add_u32_e32 v51, 0x18000, v51
	ds_read_b128 v[104:107], v98
	ds_read_b128 v[108:111], v51
	v_or_b32_e32 v99, 50, v90
	s_waitcnt lgkmcnt(2)
	v_add_f32_e32 v51, v94, v95
	v_mul_f32_e32 v94, 0xbfb8aa3b, v100
	v_exp_f32_e32 v94, v94
	v_add_f32_e32 v95, v96, v97
	v_add_f32_e32 v51, v51, v95
	s_waitcnt lgkmcnt(0)
	v_fmac_f32_e32 v51, v104, v108
	v_max_f32_e64 v51, |v51|, v94
	v_rcp_f32_e32 v51, v51
	v_fma_f32 v44, v44, v104, v68
	v_mov_b32_e32 v68, v0
	v_or_b32_e32 v96, 49, v90
	v_mul_f32_e32 v51, v44, v51
	v_mul_f32_e32 v44, v51, v51
	v_fma_f32 v45, v45, v105, v69
	v_fmac_f32_e32 v71, v47, v107
	v_mov_b32_dpp v68, v44 row_ror:8 row_mask:0xf bank_mask:0xf
	v_fmac_f32_e32 v68, v51, v51
	v_mov_b32_e32 v47, v0
	v_mov_b32_e32 v98, v0
	v_add_f32_dpp v44, v68, v68 row_ror:4 row_mask:0xf bank_mask:0xf bound_ctrl:1
	v_lshl_add_u32 v68, v96, 4, s53
	v_add_f32_dpp v94, v44, v44 row_ror:2 row_mask:0xf bank_mask:0xf bound_ctrl:1
	v_lshl_add_u32 v44, v99, 4, s53
	v_mul_f32_e32 v68, 0xbfb8aa3b, v101
	v_exp_f32_e32 v68, v68
	s_waitcnt lgkmcnt(1)
	v_add_f32_e32 v44, v198, v199
	v_add_f32_e32 v95, v200, v201
	v_add_f32_e32 v44, v44, v95
	v_fmac_f32_e32 v44, v105, v109
	v_max_f32_e64 v44, |v44|, v68
	v_rcp_f32_e32 v44, v44
	s_waitcnt lgkmcnt(0)
	v_add_f32_e32 v69, v204, v205
	v_or_b32_e32 v101, 51, v90
	v_mov_b32_e32 v95, v0
	v_mul_f32_e32 v68, v45, v44
	v_mul_f32_e32 v44, v68, v68
	v_mov_b32_e32 v45, v0
	v_mov_b32_e32 v100, v0
	v_mov_b32_dpp v95, v94 row_ror:1 row_mask:0xf bank_mask:0xf
	v_mov_b32_dpp v45, v44 row_ror:8 row_mask:0xf bank_mask:0xf
	v_fmac_f32_e32 v45, v68, v68
	s_nop 1
	v_add_f32_dpp v44, v45, v45 row_ror:4 row_mask:0xf bank_mask:0xf bound_ctrl:1
	v_mul_f32_e32 v45, 0xbfb8aa3b, v102
	v_exp_f32_e32 v45, v45
	v_add_f32_dpp v97, v44, v44 row_ror:2 row_mask:0xf bank_mask:0xf bound_ctrl:1
	v_add_f32_e32 v44, v202, v203
	v_add_f32_e32 v44, v44, v69
	v_fmac_f32_e32 v44, v106, v110
	v_max_f32_e64 v44, |v44|, v45
	v_rcp_f32_e32 v44, v44
	v_fma_f32 v45, v46, v106, v70
	v_lshl_add_u32 v69, v101, 4, s53
	v_mov_b32_e32 v46, v0
	v_mul_f32_e32 v45, v45, v44
	v_mul_f32_e32 v44, v45, v45
	v_mov_b32_e32 v102, v0
	v_mov_b32_dpp v46, v44 row_ror:8 row_mask:0xf bank_mask:0xf
	v_fmac_f32_e32 v46, v45, v45
	v_mov_b32_dpp v98, v97 row_ror:1 row_mask:0xf bank_mask:0xf
	s_waitcnt lgkmcnt(0)
	v_add_f32_e32 v69, v208, v209
	v_add_f32_dpp v44, v46, v46 row_ror:4 row_mask:0xf bank_mask:0xf bound_ctrl:1
	v_mul_f32_e32 v46, 0xbfb8aa3b, v103
	v_exp_f32_e32 v46, v46
	v_add_f32_dpp v90, v44, v44 row_ror:2 row_mask:0xf bank_mask:0xf bound_ctrl:1
	v_add_f32_e32 v44, v206, v207
	v_add_f32_e32 v44, v44, v69
	v_fmac_f32_e32 v44, v107, v111
	v_max_f32_e64 v44, |v44|, v46
	v_rcp_f32_e32 v44, v44
	v_mov_b32_dpp v100, v90 row_ror:1 row_mask:0xf bank_mask:0xf
	v_lshlrev_b32_e32 v70, 5, v75
	v_lshlrev_b32_e32 v69, 5, v96
	v_mul_f32_e32 v44, v71, v44
	v_mul_f32_e32 v46, v44, v44
	s_nop 1
	v_mov_b32_dpp v47, v46 row_ror:8 row_mask:0xf bank_mask:0xf
	v_fmac_f32_e32 v47, v44, v44
	s_nop 1
	v_add_f32_dpp v46, v47, v47 row_ror:4 row_mask:0xf bank_mask:0xf bound_ctrl:1
	v_lshlrev_b32_e32 v47, 5, v99
	s_nop 0
	v_add_f32_dpp v71, v46, v46 row_ror:2 row_mask:0xf bank_mask:0xf bound_ctrl:1
	v_lshlrev_b32_e32 v46, 5, v101
	s_nop 0
	v_mov_b32_dpp v102, v71 row_ror:1 row_mask:0xf bank_mask:0xf
	s_and_saveexec_b64 s[0:1], vcc
	s_xor_b64 s[0:1], exec, s[0:1]
	v_lshlrev_b32_e32 v70, 5, v75
	v_lshlrev_b32_e32 v69, 5, v96
	v_lshlrev_b32_e32 v47, 5, v99
	v_lshlrev_b32_e32 v46, 5, v101
	s_andn2_saveexec_b64 s[0:1], s[0:1]
	s_cbranch_execz .LBB0_704
	v_add_f32_e32 v94, v94, v95
	v_add_u32_e32 v95, v91, v70
	v_add_f32_e32 v75, v90, v100
	v_add_f32_e32 v90, v97, v98
	ds_write_b32 v95, v94
	v_add_u32_e32 v94, v91, v69
	ds_write_b32 v94, v90
	v_add_u32_e32 v90, v91, v47
	v_add_f32_e32 v71, v71, v102
	ds_write_b32 v90, v75
	v_add_u32_e32 v75, v91, v46
	ds_write_b32 v75, v71
	s_branch .LBB0_704
